# g1 decay-section scalars hoisted out of LDS chains
# speedup vs baseline: 1.1185x; 1.0025x over previous
; #define LAS __attribute__((address_space(3)))
; __device__ __forceinline__ unsigned pk2(float lo, float hi) { const f32x2_ v = {lo, hi}; return __builtin_bit_cast(unsigned, __builtin_convertvector(v, bf16x2_)); }
; __device__ __forceinline__ f32x4 mfma16(bf16x8 a, bf16x8 b, f32x4 c) { return __builtin_amdgcn_mfma_f32_16x16x32_bf16(a, b, c, 0, 0, 0); }
; __device__ __forceinline__ void g1_phase(const PP P, int l, LAS unsigned char* lds) {
;     ...
;         if (act) {
;             { const int mi = gt >> 6, ln = gt & 63, fr = ln & 15, fq = ln >> 4;
;               bf16x8 ak[2], aq[2];
; #pragma unroll
;               for (int kk = 0; kk < 2; ++kk) { const LAS float* pk = ks + (16 * mi + fr) * 65 + 32 * kk + fq * 8; const LAS float* pq = qs + (16 * mi + fr) * 65 + 32 * kk + fq * 8;
;                   u32x4 wk, wq; wk.x = pk2(pk[0], pk[1]); wk.y = pk2(pk[2], pk[3]); wk.z = pk2(pk[4], pk[5]); wk.w = pk2(pk[6], pk[7]);
;                   wq.x = pk2(pq[0], pq[1]); wq.y = pk2(pq[2], pq[3]); wq.z = pk2(pq[4], pq[5]); wq.w = pk2(pq[6], pq[7]);
;                   ak[kk] = __builtin_bit_cast(bf16x8, wk); aq[kk] = __builtin_bit_cast(bf16x8, wq); }
; #pragma unroll
;               for (int nj = 0; nj < 4; ++nj) { f32x4 ckk = {0.f, 0.f, 0.f, 0.f}, cqk = {0.f, 0.f, 0.f, 0.f};
;                   if (nj <= mi && 16 * mi < L) {
; #pragma unroll
;                       for (int kk = 0; kk < 2; ++kk) { const LAS float* pb = ks + (16 * nj + fr) * 65 + 32 * kk + fq * 8;
;                           u32x4 wb; wb.x = pk2(pb[0], pb[1]); wb.y = pk2(pb[2], pb[3]); wb.z = pk2(pb[4], pb[5]); wb.w = pk2(pb[6], pb[7]);
;                           const bf16x8 bfr = __builtin_bit_cast(bf16x8, wb); ckk = mfma16(ak[kk], bfr, ckk); cqk = mfma16(aq[kk], bfr, cqk); } }
.LBB0_520:
	s_or_b64 exec, exec, s[26:27]
	s_waitcnt lgkmcnt(0)
	s_barrier
	ds_read_b32 v222, v91
	ds_read_b32 v223, v92
	ds_read_b32 v224, v93
	ds_read_b32 v225, v95
	ds_read_b32 v226, v96
	ds_read_b32 v227, v97
	ds_read_b32 v228, v98
	ds_read_b32 v229, v99
	ds_read_b32 v230, v100
	ds_read_b32 v231, v101
	ds_read_b32 v232, v104
	ds_read_b32 v233, v107
	s_waitcnt lgkmcnt(0)
	v_cndmask_b32_e64 v69, 0, v12, s[76:77]
	v_mov_b64_e32 v[0:1], s[24:25]
	s_mov_b32 s26, 0xc100
	v_mad_i64_i32 v[70:71], s[26:27], v69, s26, v[0:1]
	s_and_saveexec_b64 s[26:27], s[76:77]
	s_cbranch_execz .LBB0_594
	v_add_u32_e32 v0, 0x4100, v89
	v_add_u32_e32 v2, 0x4108, v89
	v_add_u32_e32 v4, 0x4110, v89
	ds_read2_b32 v[0:1], v0 offset1:1
	ds_read2_b32 v[2:3], v2 offset1:1
	ds_read2_b32 v[4:5], v4 offset1:1
	s_waitcnt vmcnt(2)
	v_add_u32_e32 v6, 0x4118, v89
	s_waitcnt vmcnt(1)
	ds_read2_b32 v[6:7], v6 offset1:1
	s_waitcnt lgkmcnt(3)
	v_cvt_pk_bf16_f32 v8, v0, v1
	s_waitcnt lgkmcnt(2)
	v_cvt_pk_bf16_f32 v9, v2, v3
	s_waitcnt lgkmcnt(1)
	v_cvt_pk_bf16_f32 v10, v4, v5
	ds_read2_b32 v[0:1], v89 offset1:1
	ds_read2_b32 v[2:3], v89 offset0:2 offset1:3
	ds_read2_b32 v[4:5], v89 offset0:4 offset1:5
	s_waitcnt vmcnt(0)
	ds_read2_b32 v[16:17], v89 offset0:6 offset1:7
	s_waitcnt lgkmcnt(4)
	v_cvt_pk_bf16_f32 v11, v6, v7
	s_waitcnt lgkmcnt(3)
	v_cvt_pk_bf16_f32 v12, v0, v1
	s_waitcnt lgkmcnt(2)
	v_cvt_pk_bf16_f32 v13, v2, v3
	s_waitcnt lgkmcnt(1)
	v_cvt_pk_bf16_f32 v14, v4, v5
	v_add_u32_e32 v0, 0x4180, v89
	v_add_u32_e32 v2, 0x4188, v89
	v_add_u32_e32 v4, 0x4190, v89
	ds_read2_b32 v[0:1], v0 offset1:1
	ds_read2_b32 v[2:3], v2 offset1:1
	ds_read2_b32 v[4:5], v4 offset1:1
	v_add_u32_e32 v6, 0x4198, v89
	s_waitcnt lgkmcnt(3)
	v_cvt_pk_bf16_f32 v15, v16, v17
	ds_read2_b32 v[6:7], v6 offset1:1
	s_waitcnt lgkmcnt(3)
	v_cvt_pk_bf16_f32 v0, v0, v1
	s_waitcnt lgkmcnt(2)
	v_cvt_pk_bf16_f32 v1, v2, v3
	s_waitcnt lgkmcnt(1)
	v_cvt_pk_bf16_f32 v2, v4, v5
	ds_read2_b32 v[4:5], v89 offset0:32 offset1:33
	ds_read2_b32 v[16:17], v89 offset0:34 offset1:35
	ds_read2_b32 v[18:19], v89 offset0:36 offset1:37
	ds_read2_b32 v[20:21], v89 offset0:38 offset1:39
	s_waitcnt lgkmcnt(4)
	v_cvt_pk_bf16_f32 v3, v6, v7
	s_waitcnt lgkmcnt(3)
	v_cvt_pk_bf16_f32 v4, v4, v5
	s_waitcnt lgkmcnt(2)
	v_cvt_pk_bf16_f32 v5, v16, v17
	s_waitcnt lgkmcnt(1)
	v_cvt_pk_bf16_f32 v6, v18, v19
	s_waitcnt lgkmcnt(0)
	v_cvt_pk_bf16_f32 v7, v20, v21
	v_cmp_lt_u32_e32 vcc, v87, v68
	v_mov_b32_e32 v35, 0
	v_mov_b32_e32 v20, 0
	v_mov_b32_e32 v21, 0
	v_mov_b32_e32 v22, 0
	v_mov_b32_e32 v23, 0
	v_mov_b32_e32 v16, 0
	v_mov_b32_e32 v17, 0
	v_mov_b32_e32 v18, 0
	v_mov_b32_e32 v19, 0
	s_and_saveexec_b64 s[78:79], vcc
	s_cbranch_execz .LBB0_523
	v_add_u32_e32 v16, 0x4100, v105
	ds_read2_b32 v[16:17], v16 offset1:1
	v_add_u32_e32 v37, 0x4180, v105
	ds_read2_b32 v[72:73], v37 offset1:1
	v_add_u32_e32 v37, 0x4188, v105
	ds_read2_b32 v[74:75], v37 offset1:1
	s_waitcnt lgkmcnt(2)
	v_cvt_pk_bf16_f32 v16, v16, v17
	v_add_u32_e32 v17, 0x4108, v105
	ds_read2_b32 v[18:19], v17 offset1:1
	v_add_u32_e32 v37, 0x4190, v105
	s_waitcnt lgkmcnt(2)
	v_cvt_pk_bf16_f32 v72, v72, v73
	s_waitcnt lgkmcnt(1)
	v_cvt_pk_bf16_f32 v73, v74, v75
	ds_read2_b32 v[74:75], v37 offset1:1
	s_waitcnt lgkmcnt(1)
	v_cvt_pk_bf16_f32 v17, v18, v19
	v_add_u32_e32 v18, 0x4110, v105
	ds_read2_b32 v[18:19], v18 offset1:1
	v_add_u32_e32 v37, 0x4198, v105
	s_waitcnt lgkmcnt(1)
	v_cvt_pk_bf16_f32 v74, v74, v75
	ds_read2_b32 v[76:77], v37 offset1:1
	s_waitcnt lgkmcnt(1)
	v_cvt_pk_bf16_f32 v18, v18, v19
	v_add_u32_e32 v19, 0x4118, v105
	ds_read2_b32 v[20:21], v19 offset1:1
	s_waitcnt lgkmcnt(1)
	v_cvt_pk_bf16_f32 v75, v76, v77
	s_waitcnt lgkmcnt(0)
	v_cvt_pk_bf16_f32 v19, v20, v21
	s_nop 1
	v_mfma_f32_16x16x32_bf16 v[20:23], v[8:11], v[16:19], 0
	v_mfma_f32_16x16x32_bf16 v[16:19], v[12:15], v[16:19], 0
	v_mfma_f32_16x16x32_bf16 v[20:23], v[0:3], v[72:75], v[20:23]
	v_mfma_f32_16x16x32_bf16 v[16:19], v[4:7], v[72:75], v[16:19]
; __device__ __forceinline__ unsigned f2bf(float f) { const f32x2_ v = {f, 0.f}; const bf16x2_ b = __builtin_convertvector(v, bf16x2_); return __builtin_bit_cast(unsigned, b) & 0xffffu; }
; __device__ __forceinline__ void g1_phase(const PP P, int l, LAS unsigned char* lds) {
;     ...
;                   const int jc = 16 * nj + fr; const float gj = Gs[jc];
; #pragma unroll
;                   for (int j = 0; j < 4; ++j) { const int i = 16 * mi + fq * 4 + j; const float dec = (i >= jc) ? __expf(Gs[i] - gj) : 0.f;
;                       As[i * 64 + jc] = (i > jc) ? bs[i] * ckk[j] * dec : 0.f; QKd[i * 64 + jc] = (bf16)f2bf(cqk[j] * dec); } } }
.LBB0_523:
	s_or_b64 exec, exec, s[78:79]
	v_mov_b32_e32 v39, v222
	s_and_saveexec_b64 s[28:29], s[14:15]
	s_cbranch_execz .LBB0_525
	v_mov_b32_e32 v35, v223
	s_waitcnt lgkmcnt(0)
	v_sub_f32_e32 v35, v35, v39
	v_mul_f32_e32 v35, 0x3fb8aa3b, v35
	v_exp_f32_e32 v35, v35
.LBB0_525:
	s_or_b64 exec, exec, s[28:29]
	v_mov_b32_e32 v37, 0
	v_mov_b32_e32 v41, 0
	s_mov_b64 s[28:29], exec
	v_readlane_b32 s68, v254, 21
	v_readlane_b32 s69, v254, 22
	s_and_b64 s[68:69], s[28:29], s[68:69]
	s_mov_b64 exec, s[68:69]
	s_cbranch_execz .LBB0_527
	v_mov_b32_e32 v41, v224
	s_waitcnt lgkmcnt(0)
	v_mul_f32_e32 v20, v20, v41
	v_mul_f32_e32 v41, v35, v20
.LBB0_527:
	s_or_b64 exec, exec, s[28:29]
	s_mov_b64 s[28:29], 0x2000
	v_lshl_add_u64 v[72:73], v[70:71], 0, s[28:29]
	v_mul_f32_e32 v16, v16, v35
	v_cvt_pk_bf16_f32 v16, v16, s0
	v_lshl_add_u64 v[74:75], v[72:73], 0, v[24:25]
	ds_write_b32 v94, v41 offset:49920
	global_store_short v[74:75], v16, off
	s_mov_b64 s[28:29], exec
	v_readlane_b32 s68, v254, 23
	v_readlane_b32 s69, v254, 24
	s_and_b64 s[68:69], s[28:29], s[68:69]
	s_mov_b64 exec, s[68:69]
	s_cbranch_execz .LBB0_529
	v_mov_b32_e32 v16, v225
	s_waitcnt lgkmcnt(0)
	v_sub_f32_e32 v16, v16, v39
	v_mul_f32_e32 v16, 0x3fb8aa3b, v16
	v_exp_f32_e32 v37, v16
.LBB0_529:
	s_or_b64 exec, exec, s[28:29]
	v_mov_b32_e32 v16, 0
	v_mov_b32_e32 v20, 0
	s_and_saveexec_b64 s[28:29], s[14:15]
	s_cbranch_execz .LBB0_531
	v_mov_b32_e32 v20, v226
	s_waitcnt lgkmcnt(0)
	v_mul_f32_e32 v20, v21, v20
	v_mul_f32_e32 v20, v37, v20
.LBB0_531:
	s_or_b64 exec, exec, s[28:29]
	v_mul_f32_e32 v17, v17, v37
	v_mov_b32_e32 v35, v25
	ds_write_b32 v117, v20 offset:49920
	v_cvt_pk_bf16_f32 v17, v17, s0
	v_lshl_add_u64 v[20:21], v[72:73], 0, v[34:35]
	global_store_short v[20:21], v17, off
	s_mov_b64 s[28:29], exec
	v_readlane_b32 s68, v254, 25
	v_readlane_b32 s69, v254, 26
	s_and_b64 s[68:69], s[28:29], s[68:69]
	s_mov_b64 exec, s[68:69]
	s_cbranch_execz .LBB0_533
	v_mov_b32_e32 v16, v227
	s_waitcnt lgkmcnt(0)
	v_sub_f32_e32 v16, v16, v39
	v_mul_f32_e32 v16, 0x3fb8aa3b, v16
	v_exp_f32_e32 v16, v16
.LBB0_533:
	s_or_b64 exec, exec, s[28:29]
	v_mov_b32_e32 v17, 0
	v_mov_b32_e32 v20, 0
	s_mov_b64 s[28:29], exec
	v_readlane_b32 s68, v254, 27
	v_readlane_b32 s69, v254, 28
	s_and_b64 s[68:69], s[28:29], s[68:69]
	s_mov_b64 exec, s[68:69]
	s_cbranch_execz .LBB0_535
	v_mov_b32_e32 v20, v228
	s_waitcnt lgkmcnt(0)
	v_mul_f32_e32 v20, v22, v20
	v_mul_f32_e32 v20, v16, v20
.LBB0_535:
	s_or_b64 exec, exec, s[28:29]
	v_mul_f32_e32 v16, v18, v16
	v_mov_b32_e32 v37, v25
	ds_write_b32 v118, v20 offset:49920
	v_cvt_pk_bf16_f32 v16, v16, s0
	v_lshl_add_u64 v[20:21], v[72:73], 0, v[36:37]
	global_store_short v[20:21], v16, off
	s_mov_b64 s[28:29], exec
	v_readlane_b32 s68, v254, 29
	v_readlane_b32 s69, v254, 30
	s_and_b64 s[68:69], s[28:29], s[68:69]
	s_mov_b64 exec, s[68:69]
	s_cbranch_execz .LBB0_537
	v_mov_b32_e32 v16, v229
	s_waitcnt lgkmcnt(0)
	v_sub_f32_e32 v16, v16, v39
	v_mul_f32_e32 v16, 0x3fb8aa3b, v16
	v_exp_f32_e32 v17, v16
.LBB0_537:
	s_or_b64 exec, exec, s[28:29]
	v_mov_b32_e32 v16, 0
	v_mov_b32_e32 v18, 0
	s_mov_b64 s[28:29], exec
	v_readlane_b32 s68, v254, 31
	v_readlane_b32 s69, v254, 32
	s_and_b64 s[68:69], s[28:29], s[68:69]
	s_mov_b64 exec, s[68:69]
	s_cbranch_execz .LBB0_539
	v_mov_b32_e32 v18, v230
	s_waitcnt lgkmcnt(0)
	v_mul_f32_e32 v18, v23, v18
	v_mul_f32_e32 v18, v17, v18

; __device__ __forceinline__ unsigned f2bf(float f) { const f32x2_ v = {f, 0.f}; const bf16x2_ b = __builtin_convertvector(v, bf16x2_); return __builtin_bit_cast(unsigned, b) & 0xffffu; }
; __device__ __forceinline__ void g1_phase(const PP P, int l, LAS unsigned char* lds) {
;     ...
;                   const int jc = 16 * nj + fr; const float gj = Gs[jc];
; #pragma unroll
;                   for (int j = 0; j < 4; ++j) { const int i = 16 * mi + fq * 4 + j; const float dec = (i >= jc) ? __expf(Gs[i] - gj) : 0.f;
;                       As[i * 64 + jc] = (i > jc) ? bs[i] * ckk[j] * dec : 0.f; QKd[i * 64 + jc] = (bf16)f2bf(cqk[j] * dec); } } }
.LBB0_541:
	s_or_b64 exec, exec, s[78:79]
	v_mov_b32_e32 v35, v231
	v_mov_b32_e32 v37, 0
	v_mov_b32_e32 v39, 0
	s_and_saveexec_b64 s[28:29], s[34:35]
	s_cbranch_execz .LBB0_543
	v_mov_b32_e32 v39, v223
	s_waitcnt lgkmcnt(0)
	v_sub_f32_e32 v39, v39, v35
	v_mul_f32_e32 v39, 0x3fb8aa3b, v39
	v_exp_f32_e32 v39, v39
.LBB0_543:
	s_or_b64 exec, exec, s[28:29]
	s_and_saveexec_b64 s[28:29], s[36:37]
	s_cbranch_execz .LBB0_545
	v_mov_b32_e32 v37, v224
	s_waitcnt lgkmcnt(0)
	v_mul_f32_e32 v16, v16, v37
	v_mul_f32_e32 v37, v39, v16
.LBB0_545:
	s_or_b64 exec, exec, s[28:29]
	v_mul_f32_e32 v16, v20, v39
	v_mov_b32_e32 v41, v25
	v_cvt_pk_bf16_f32 v16, v16, s0
	v_lshl_add_u64 v[74:75], v[72:73], 0, v[40:41]
	global_store_short v[74:75], v16, off
	v_mov_b32_e32 v16, 0
	v_mov_b32_e32 v20, 0
	ds_write_b32 v94, v37 offset:49984
	s_and_saveexec_b64 s[28:29], s[46:47]
	s_cbranch_execz .LBB0_547
	v_mov_b32_e32 v20, v225
	s_waitcnt lgkmcnt(0)
	v_sub_f32_e32 v20, v20, v35
	v_mul_f32_e32 v20, 0x3fb8aa3b, v20
	v_exp_f32_e32 v20, v20
.LBB0_547:
	s_or_b64 exec, exec, s[28:29]
	s_and_saveexec_b64 s[28:29], s[34:35]
	s_cbranch_execz .LBB0_549
	v_mov_b32_e32 v16, v226
	s_waitcnt lgkmcnt(0)
	v_mul_f32_e32 v16, v17, v16
	v_mul_f32_e32 v16, v20, v16
.LBB0_549:
	s_or_b64 exec, exec, s[28:29]
	ds_write_b32 v117, v16 offset:49984
	v_mul_f32_e32 v16, v21, v20
	v_mov_b32_e32 v43, v25
	v_cvt_pk_bf16_f32 v20, v16, s0
	v_lshl_add_u64 v[16:17], v[72:73], 0, v[42:43]
	global_store_short v[16:17], v20, off
	v_mov_b32_e32 v16, 0
	v_mov_b32_e32 v17, 0
	s_and_saveexec_b64 s[28:29], s[16:17]
	s_cbranch_execz .LBB0_551
	v_mov_b32_e32 v17, v227
	s_waitcnt lgkmcnt(0)
	v_sub_f32_e32 v17, v17, v35
	v_mul_f32_e32 v17, 0x3fb8aa3b, v17
	v_exp_f32_e32 v17, v17
.LBB0_551:
	s_or_b64 exec, exec, s[28:29]
	s_and_saveexec_b64 s[28:29], s[18:19]
	s_cbranch_execz .LBB0_553
	v_mov_b32_e32 v16, v228
	s_waitcnt lgkmcnt(0)
	v_mul_f32_e32 v16, v18, v16
	v_mul_f32_e32 v16, v17, v16
.LBB0_553:
	s_or_b64 exec, exec, s[28:29]
	ds_write_b32 v118, v16 offset:49984
	v_mul_f32_e32 v16, v22, v17
	v_mov_b32_e32 v45, v25
	v_cvt_pk_bf16_f32 v18, v16, s0
	v_lshl_add_u64 v[16:17], v[72:73], 0, v[44:45]
	global_store_short v[16:17], v18, off
	v_mov_b32_e32 v16, 0
	v_mov_b32_e32 v17, 0
	s_and_saveexec_b64 s[28:29], s[64:65]
	s_cbranch_execz .LBB0_555
	v_mov_b32_e32 v17, v229
	s_waitcnt lgkmcnt(0)
	v_sub_f32_e32 v17, v17, v35
	v_mul_f32_e32 v17, 0x3fb8aa3b, v17
	v_exp_f32_e32 v17, v17
.LBB0_555:
	s_or_b64 exec, exec, s[28:29]
	s_and_saveexec_b64 s[28:29], s[66:67]
	s_cbranch_execz .LBB0_557
	v_mov_b32_e32 v16, v230
	s_waitcnt lgkmcnt(0)
	v_mul_f32_e32 v16, v19, v16
	v_mul_f32_e32 v16, v17, v16

; __device__ __forceinline__ unsigned f2bf(float f) { const f32x2_ v = {f, 0.f}; const bf16x2_ b = __builtin_convertvector(v, bf16x2_); return __builtin_bit_cast(unsigned, b) & 0xffffu; }
; __device__ __forceinline__ void g1_phase(const PP P, int l, LAS unsigned char* lds) {
;     ...
;                   const int jc = 16 * nj + fr; const float gj = Gs[jc];
; #pragma unroll
;                   for (int j = 0; j < 4; ++j) { const int i = 16 * mi + fq * 4 + j; const float dec = (i >= jc) ? __expf(Gs[i] - gj) : 0.f;
;                       As[i * 64 + jc] = (i > jc) ? bs[i] * ckk[j] * dec : 0.f; QKd[i * 64 + jc] = (bf16)f2bf(cqk[j] * dec); } } }
.LBB0_559:
	s_or_b64 exec, exec, s[78:79]
	v_mov_b32_e32 v37, v232
	s_and_saveexec_b64 s[28:29], s[38:39]
	s_cbranch_execz .LBB0_561
	v_mov_b32_e32 v35, v223
	s_waitcnt lgkmcnt(0)
	v_sub_f32_e32 v35, v35, v37
	v_mul_f32_e32 v35, 0x3fb8aa3b, v35
	v_exp_f32_e32 v35, v35
.LBB0_561:
	s_or_b64 exec, exec, s[28:29]
	v_mov_b32_e32 v39, 0
	v_mov_b32_e32 v41, 0
	s_and_saveexec_b64 s[28:29], s[40:41]
	s_cbranch_execz .LBB0_563
	v_mov_b32_e32 v41, v224
	s_waitcnt lgkmcnt(0)
	v_mul_f32_e32 v20, v20, v41
	v_mul_f32_e32 v41, v35, v20
.LBB0_563:
	s_or_b64 exec, exec, s[28:29]
	v_mul_f32_e32 v16, v16, v35
	v_mov_b32_e32 v49, v25
	v_cvt_pk_bf16_f32 v16, v16, s0
	v_lshl_add_u64 v[74:75], v[72:73], 0, v[48:49]
	ds_write_b32 v94, v41 offset:50048
	global_store_short v[74:75], v16, off
	s_and_saveexec_b64 s[28:29], s[52:53]
	s_cbranch_execz .LBB0_565
	v_mov_b32_e32 v16, v225
	s_waitcnt lgkmcnt(0)
	v_sub_f32_e32 v16, v16, v37
	v_mul_f32_e32 v16, 0x3fb8aa3b, v16
	v_exp_f32_e32 v39, v16
.LBB0_565:
	s_or_b64 exec, exec, s[28:29]
	v_mov_b32_e32 v16, 0
	v_mov_b32_e32 v20, 0
	s_and_saveexec_b64 s[28:29], s[38:39]
	s_cbranch_execz .LBB0_567
	v_mov_b32_e32 v20, v226
	s_waitcnt lgkmcnt(0)
	v_mul_f32_e32 v20, v21, v20
	v_mul_f32_e32 v20, v39, v20
.LBB0_567:
	s_or_b64 exec, exec, s[28:29]
	v_mul_f32_e32 v17, v17, v39
	v_mov_b32_e32 v51, v25
	ds_write_b32 v117, v20 offset:50048
	v_cvt_pk_bf16_f32 v17, v17, s0
	v_lshl_add_u64 v[20:21], v[72:73], 0, v[50:51]
	global_store_short v[20:21], v17, off
	s_and_saveexec_b64 s[28:29], s[54:55]
	s_cbranch_execz .LBB0_569
	v_mov_b32_e32 v16, v227
	s_waitcnt lgkmcnt(0)
	v_sub_f32_e32 v16, v16, v37
	v_mul_f32_e32 v16, 0x3fb8aa3b, v16
	v_exp_f32_e32 v16, v16
.LBB0_569:
	s_or_b64 exec, exec, s[28:29]
	v_mov_b32_e32 v17, 0
	v_mov_b32_e32 v20, 0
	s_and_saveexec_b64 s[28:29], s[56:57]
	s_cbranch_execz .LBB0_571
	v_mov_b32_e32 v20, v228
	s_waitcnt lgkmcnt(0)
	v_mul_f32_e32 v20, v22, v20
	v_mul_f32_e32 v20, v16, v20
.LBB0_571:
	s_or_b64 exec, exec, s[28:29]
	v_mul_f32_e32 v16, v18, v16
	v_mov_b32_e32 v53, v25
	ds_write_b32 v118, v20 offset:50048
	v_cvt_pk_bf16_f32 v16, v16, s0
	v_lshl_add_u64 v[20:21], v[72:73], 0, v[52:53]
	global_store_short v[20:21], v16, off
	s_and_saveexec_b64 s[28:29], s[30:31]
	s_cbranch_execz .LBB0_573
	v_mov_b32_e32 v16, v229
	s_waitcnt lgkmcnt(0)
	v_sub_f32_e32 v16, v16, v37
	v_mul_f32_e32 v16, 0x3fb8aa3b, v16
	v_exp_f32_e32 v17, v16
.LBB0_573:
	s_or_b64 exec, exec, s[28:29]
	v_mov_b32_e32 v16, 0
	v_mov_b32_e32 v18, 0
	s_and_saveexec_b64 s[28:29], s[70:71]
	s_cbranch_execz .LBB0_575
	v_mov_b32_e32 v18, v230
	s_waitcnt lgkmcnt(0)
	v_mul_f32_e32 v18, v23, v18
	v_mul_f32_e32 v18, v17, v18

; __device__ __forceinline__ unsigned f2bf(float f) { const f32x2_ v = {f, 0.f}; const bf16x2_ b = __builtin_convertvector(v, bf16x2_); return __builtin_bit_cast(unsigned, b) & 0xffffu; }
; __device__ __forceinline__ void g1_phase(const PP P, int l, LAS unsigned char* lds) {
;     ...
;                   const int jc = 16 * nj + fr; const float gj = Gs[jc];
; #pragma unroll
;                   for (int j = 0; j < 4; ++j) { const int i = 16 * mi + fq * 4 + j; const float dec = (i >= jc) ? __expf(Gs[i] - gj) : 0.f;
;                       As[i * 64 + jc] = (i > jc) ? bs[i] * ckk[j] * dec : 0.f; QKd[i * 64 + jc] = (bf16)f2bf(cqk[j] * dec); } } }
.LBB0_577:
	s_or_b64 exec, exec, s[78:79]
	v_mov_b32_e32 v0, v233
	v_mov_b32_e32 v1, 0
	v_mov_b32_e32 v2, 0
	s_and_saveexec_b64 s[28:29], s[42:43]
	s_cbranch_execz .LBB0_579
	v_mov_b32_e32 v2, v223
	s_waitcnt lgkmcnt(0)
	v_sub_f32_e32 v2, v2, v0
	v_mul_f32_e32 v2, 0x3fb8aa3b, v2
	v_exp_f32_e32 v2, v2
.LBB0_579:
	s_or_b64 exec, exec, s[28:29]
	s_and_saveexec_b64 s[28:29], s[44:45]
	s_cbranch_execz .LBB0_581
	v_mov_b32_e32 v1, v224
	s_waitcnt lgkmcnt(0)
	v_mul_f32_e32 v1, v16, v1
	v_mul_f32_e32 v1, v2, v1
.LBB0_581:
	s_or_b64 exec, exec, s[28:29]
	ds_write_b32 v94, v1 offset:50112
	v_mul_f32_e32 v1, v20, v2
	v_mov_b32_e32 v57, v25
	v_cvt_pk_bf16_f32 v1, v1, s0
	v_lshl_add_u64 v[2:3], v[72:73], 0, v[56:57]
	global_store_short v[2:3], v1, off
	v_mov_b32_e32 v1, 0
	v_mov_b32_e32 v2, 0
	s_and_saveexec_b64 s[28:29], s[58:59]
	s_cbranch_execz .LBB0_583
	v_mov_b32_e32 v2, v225
	s_waitcnt lgkmcnt(0)
	v_sub_f32_e32 v2, v2, v0
	v_mul_f32_e32 v2, 0x3fb8aa3b, v2
	v_exp_f32_e32 v2, v2
.LBB0_583:
	s_or_b64 exec, exec, s[28:29]
	s_and_saveexec_b64 s[28:29], s[42:43]
	s_cbranch_execz .LBB0_585
	v_mov_b32_e32 v1, v226
	s_waitcnt lgkmcnt(0)
	v_mul_f32_e32 v1, v17, v1
	v_mul_f32_e32 v1, v2, v1
.LBB0_585:
	s_or_b64 exec, exec, s[28:29]
	ds_write_b32 v117, v1 offset:50112
	v_mul_f32_e32 v1, v21, v2
	v_mov_b32_e32 v59, v25
	v_cvt_pk_bf16_f32 v1, v1, s0
	v_lshl_add_u64 v[2:3], v[72:73], 0, v[58:59]
	global_store_short v[2:3], v1, off
	v_mov_b32_e32 v1, 0
	v_mov_b32_e32 v2, 0
	s_and_saveexec_b64 s[28:29], s[60:61]
	s_cbranch_execz .LBB0_587
	v_mov_b32_e32 v2, v227
	s_waitcnt lgkmcnt(0)
	v_sub_f32_e32 v2, v2, v0
	v_mul_f32_e32 v2, 0x3fb8aa3b, v2
	v_exp_f32_e32 v2, v2
.LBB0_587:
	s_or_b64 exec, exec, s[28:29]
	s_and_saveexec_b64 s[28:29], s[2:3]
	s_cbranch_execz .LBB0_589
	v_mov_b32_e32 v1, v228
	s_waitcnt lgkmcnt(0)
	v_mul_f32_e32 v1, v18, v1
	v_mul_f32_e32 v1, v2, v1
.LBB0_589:
	s_or_b64 exec, exec, s[28:29]
	ds_write_b32 v118, v1 offset:50112
	v_mul_f32_e32 v1, v22, v2
	v_mov_b32_e32 v61, v25
	v_cvt_pk_bf16_f32 v1, v1, s0
	v_lshl_add_u64 v[2:3], v[72:73], 0, v[60:61]
	global_store_short v[2:3], v1, off
	v_mov_b32_e32 v1, 0
	v_mov_b32_e32 v2, 0
	s_and_saveexec_b64 s[28:29], s[72:73]
	s_cbranch_execz .LBB0_591
	v_mov_b32_e32 v2, v229
	s_waitcnt lgkmcnt(0)
	v_sub_f32_e32 v0, v2, v0
	v_mul_f32_e32 v0, 0x3fb8aa3b, v0
	v_exp_f32_e32 v2, v0
.LBB0_591:
	s_or_b64 exec, exec, s[28:29]
	s_and_saveexec_b64 s[28:29], s[74:75]
	s_cbranch_execz .LBB0_593
	s_waitcnt lgkmcnt(3)
	v_mov_b32_e32 v0, v230
	s_waitcnt lgkmcnt(0)
	v_mul_f32_e32 v0, v19, v0
	v_mul_f32_e32 v1, v2, v0
